# attention main loop, loop-edge rotation: the first Q.K^T MFMA of each step issued directly behind the per-tile barrier (rescale test, slot rotation, back edge and V fragment reads run in its shadow);
# baseline (speedup 1.0000x reference)
; #define WAIT_BAR(N) asm volatile("s_waitcnt vmcnt(" #N ") lgkmcnt(0)\n\ts_barrier":::"memory")
;   #define DMA_K(t,slot) glds16(ksrc+(long)(t)*KVBLK*PD,(unsigned)__builtin_amdgcn_readfirstlane(kdst+(slot)))
;   #define DMA_V(t,slot) glds16(vsrc+(long)(t)*KVBLK*PD,(unsigned)__builtin_amdgcn_readfirstlane(vdst+(slot)))
;   #define CMASK(P0,P1,t) do{int jb_=(t)-(NT-4); if(jb_>=0)cmask(P0,P1,jb_,qrel,hi);}while(0)
;   #define START(P0,P1) do{ const float rm=rowmax(P0,P1); resc=false; \
;     { const float dl=rm; mhat=fadd_s(mhat,dl); \
;       _Pragma("unroll") for(int r=0;r<16;++r){P0[r]=fsub_s(P0[r],dl);P1[r]=fsub_s(P1[r],dl);} \
;       _Pragma("unroll") for(int r=0;r<16;++r)negm[r]=-mhat; asm volatile("":"+v"(negm)); } \
;     _Pragma("unroll") for(int r=0;r<16;++r)P0[r]=__builtin_amdgcn_exp2f(P0[r]); }while(0)
;   #define ROT() do{sl_prev=sl_cur;sl_cur=sl_next;sl_next=(sl_next==(NSLOT-1)*SLOTB)?0:sl_next+SLOTB;}while(0)
;   #define CMASK(P0,P1,t) do{}while(0)
;   #define CMASK(P0,P1,t) do{int jb_=(t)-(NT-4); if(jb_>=0)cmask(P0,P1,jb_,qrel,hi);}while(0)
; template<int THRL> __device__ __forceinline__ void attn_unit(int b,int h,int qb,const bf16*Q,const bf16*__restrict__ K,const bf16*__restrict__ V,bf16*O,char*shm,const int wid){
;     ...
;   f32x16 pA0,pA1,pB0,pB1;
;   int sl_prev=0,sl_cur=0,sl_next=SLOTB;
;     ...
;   DMA_K(2,2*SLOTB);
;   WAIT_BAR(3);
;   qkt(pA0,pA1,Kbase,qr,negm,r32,hi);asm volatile("s_nop 15\n\ts_nop 7":"+v"(pA0),"+v"(pA1));CMASK(pA0,pA1,0);
;   START(pA0,pA1);
;   _Pragma("unroll") for(int r=0;r<16;++r)pA1[r]=__builtin_amdgcn_exp2f(pA1[r]);
;   WAIT_BAR(0);
;   DMA_K(3,0);DMA_V(1,SLOTB);
;   ROT();
;   kload8(kf,kp0+sl_cur);
;   WAIT_BAR(2);
.LBB0_1545:
	v_lshlrev_b32_e32 v0, 1, v210
	v_and_b32_e32 v217, 32, v0
	v_lshlrev_b32_e32 v0, 4, v210
	v_and_b32_e32 v0, 0xc0, v0
	v_lshl_or_b32 v215, v213, 8, v0
	v_add_u32_e32 v0, 0, v217
	v_add3_u32 v221, v0, v214, v215
	v_max3_f32 v0, v18, v19, v2
	v_max3_f32 v36, v20, v21, v3
	s_sub_i32 s3, 0x1000, s36
	v_max3_f32 v0, v0, v4, v5
	v_max3_f32 v36, v36, v24, v25
	s_lshr_b32 s3, s3, 6
	v_max3_f32 v0, v0, v22, v23
	v_max3_f32 v36, v36, v8, v9
	s_cmp_lg_u32 0, -1
	v_max3_f32 v0, v0, v6, v7
	v_max3_f32 v36, v36, v28, v29
	v_lshl_add_u64 v[198:199], v[34:35], 0, s[22:23]
	v_max3_f32 v0, v0, v26, v27
	v_max3_f32 v36, v36, v12, v13
	s_mov_b32 s8, 1
	v_max3_f32 v0, v0, v10, v11
	v_max3_f32 v36, v36, v32, v33
	s_mov_b32 s38, 0
	v_max3_f32 v0, v0, v30, v31
	v_max3_f32 v36, v36, v16, v17
	v_lshlrev_b32_e32 v222, 4, v213
	v_max3_f32 v0, v0, v14, v15
	s_nop 0
	v_max_f32_e32 v0, v0, v36
	s_nop 0
	v_mov_b32_e32 v36, v0
	s_nop 1
	v_permlane32_swap_b32_e32 v0, v36
	v_max_f32_e32 v0, v0, v36
	s_nop 0
	v_add_f32_e32 v219, v1, v0
	v_sub_f32_e32 v2, v2, v0
	v_sub_f32_e32 v3, v3, v0
	v_sub_f32_e32 v18, v18, v0
	v_sub_f32_e32 v19, v19, v0
	v_sub_f32_e32 v20, v20, v0
	s_nop 0
	v_xor_b32_e32 v48, 0x80000000, v219
	v_mov_b32_e32 v49, v48
	v_mov_b32_e32 v50, v48
	v_mov_b32_e32 v51, v48
	v_mov_b32_e32 v52, v48
	v_mov_b32_e32 v53, v48
	v_mov_b32_e32 v54, v48
	v_mov_b32_e32 v55, v48
	v_mov_b32_e32 v56, v48
	v_mov_b32_e32 v57, v48
	v_mov_b32_e32 v58, v48
	v_mov_b32_e32 v59, v48
	v_mov_b32_e32 v60, v48
	v_mov_b32_e32 v61, v48
	v_mov_b32_e32 v62, v48
	v_mov_b32_e32 v63, v48
	s_waitcnt vmcnt(0) lgkmcnt(0)
	s_barrier
	v_exp_f32_e32 v64, v2
	v_exp_f32_e32 v65, v3
	v_lshl_add_u64 v[2:3], v[196:197], 0, s[20:21]
	s_mov_b32 s9, m0
	s_mov_b32 m0, s46
	s_nop 0
	global_load_lds_dwordx4 v[2:3], off
	s_mov_b32 m0, s9
	s_cselect_b32 s9, 0, 0
	s_add_i32 s9, s9, s45
	s_add_i32 s9, s9, 0x8000
	s_mov_b32 s13, m0
	s_mov_b32 m0, s9
	s_nop 0
	global_load_lds_dwordx4 v[198:199], off
	s_mov_b32 m0, s13
	ds_read_b128 v[188:191], v220 offset:8192
	ds_read_b128 v[184:187], v220 offset:8704
	ds_read_b128 v[180:183], v220 offset:10240
	ds_read_b128 v[176:179], v220 offset:10752
	ds_read_b128 v[172:175], v220 offset:12288
	ds_read_b128 v[168:171], v220 offset:12800
	ds_read_b128 v[164:167], v220 offset:14336
	ds_read_b128 v[160:163], v220 offset:14848
	v_sub_f32_e32 v4, v4, v0
	v_sub_f32_e32 v21, v21, v0
	v_sub_f32_e32 v5, v5, v0
	v_sub_f32_e32 v22, v22, v0
	v_sub_f32_e32 v6, v6, v0
	v_sub_f32_e32 v23, v23, v0
	v_sub_f32_e32 v7, v7, v0
	v_sub_f32_e32 v24, v24, v0
	v_sub_f32_e32 v8, v8, v0
	v_sub_f32_e32 v25, v25, v0
	v_sub_f32_e32 v9, v9, v0
	v_sub_f32_e32 v26, v26, v0
	v_sub_f32_e32 v10, v10, v0
	v_sub_f32_e32 v27, v27, v0
	v_sub_f32_e32 v11, v11, v0
	v_sub_f32_e32 v28, v28, v0
	v_sub_f32_e32 v12, v12, v0
	v_sub_f32_e32 v29, v29, v0
	v_sub_f32_e32 v13, v13, v0
	v_sub_f32_e32 v30, v30, v0
	v_sub_f32_e32 v14, v14, v0
	v_sub_f32_e32 v31, v31, v0
	v_sub_f32_e32 v15, v15, v0
	v_sub_f32_e32 v32, v32, v0
	v_sub_f32_e32 v16, v16, v0
	v_sub_f32_e32 v33, v33, v0
	v_sub_f32_e32 v0, v17, v0
	v_exp_f32_e32 v80, v18
	v_exp_f32_e32 v81, v19
	v_exp_f32_e32 v82, v20
	v_exp_f32_e32 v83, v21
	v_exp_f32_e32 v84, v22
	v_exp_f32_e32 v85, v23
	v_exp_f32_e32 v86, v24
	v_exp_f32_e32 v87, v25
	v_exp_f32_e32 v88, v26
	v_exp_f32_e32 v89, v27
	v_exp_f32_e32 v90, v28
	v_exp_f32_e32 v91, v29
	v_exp_f32_e32 v92, v30
	v_exp_f32_e32 v93, v31
	v_exp_f32_e32 v94, v32
	v_exp_f32_e32 v95, v33
	v_exp_f32_e32 v66, v4
	v_exp_f32_e32 v67, v5
	v_exp_f32_e32 v68, v6
	v_exp_f32_e32 v69, v7
	v_exp_f32_e32 v70, v8
	v_exp_f32_e32 v71, v9
	v_exp_f32_e32 v72, v10
	v_exp_f32_e32 v73, v11
	v_exp_f32_e32 v74, v12
	v_exp_f32_e32 v75, v13
	v_exp_f32_e32 v76, v14
	v_exp_f32_e32 v77, v15
	v_exp_f32_e32 v78, v16
	v_exp_f32_e32 v79, v0
	s_waitcnt vmcnt(2) lgkmcnt(0)
	s_barrier
	s_andn2_b64 vcc, exec, s[6:7]
	v_cmp_gt_u32_e64 s[6:7], 32, v210
	s_cbranch_vccnz .LBB0_1561
	v_mov_b32_e32 v14, v1
	v_mov_b32_e32 v15, v1
	v_lshl_add_u64 v[200:201], v[34:35], 0, s[20:21]
	v_mov_b32_e32 v0, v1
	v_mov_b32_e32 v2, v1
	v_mov_b32_e32 v3, v1
	v_mov_b32_e32 v4, v1
	v_mov_b32_e32 v5, v1
	v_mov_b32_e32 v6, v1
	v_mov_b32_e32 v7, v1
	v_mov_b32_e32 v8, v1
	v_mov_b32_e32 v9, v1
	v_mov_b32_e32 v10, v1
	v_mov_b32_e32 v11, v1
	v_mov_b32_e32 v12, v1
	v_mov_b32_e32 v13, v1
	v_mov_b64_e32 v[46:47], v[14:15]
	v_mov_b64_e32 v[30:31], v[14:15]
	v_lshl_add_u32 v204, v212, 2, s48
	v_lshl_add_u64 v[202:203], v[196:197], 0, s[24:25]
	s_mov_b32 s8, 0
	s_movk_i32 s38, 0x4000
	s_movk_i32 s40, 0x2000
	v_mov_b32_e32 v223, 0
	s_mov_b32 s39, 6
	v_mov_b64_e32 v[44:45], v[12:13]
	v_mov_b64_e32 v[42:43], v[10:11]
	v_mov_b64_e32 v[40:41], v[8:9]
	v_mov_b64_e32 v[38:39], v[6:7]
	v_mov_b64_e32 v[36:37], v[4:5]
	v_mov_b64_e32 v[34:35], v[2:3]
	v_mov_b64_e32 v[32:33], v[0:1]
	v_mov_b64_e32 v[28:29], v[12:13]
	v_mov_b64_e32 v[26:27], v[10:11]
	v_mov_b64_e32 v[24:25], v[8:9]
	v_mov_b64_e32 v[22:23], v[6:7]
	v_mov_b64_e32 v[20:21], v[4:5]
	v_mov_b64_e32 v[18:19], v[2:3]
	v_mov_b64_e32 v[16:17], v[0:1]
	v_mfma_f32_32x32x16_bf16 v[112:127], v[188:191], v[148:151], v[48:63]
.LBB0_1547:
	v_add_u32_e32 v0, s8, v221
	ds_read_b64_tr_b16 v[192:193], v0 offset:24576
	ds_read_b64_tr_b16 v[194:195], v0 offset:25088
	s_waitcnt lgkmcnt(9)
	v_add_f32_e32 v2, v80, v81
	v_add_f32_e32 v2, v82, v2
	v_add_f32_e32 v2, v83, v2
	v_add_f32_e32 v2, v84, v2
	v_add_f32_e32 v2, v85, v2
	v_cvt_pk_bf16_f32 v156, v80, v81
	v_cvt_pk_bf16_f32 v157, v82, v83
	ds_read_b64_tr_b16 v[188:189], v0 offset:28672
	ds_read_b64_tr_b16 v[190:191], v0 offset:29184
	s_waitcnt lgkmcnt(10)
	v_mfma_f32_32x32x16_bf16 v[96:111], v[184:187], v[148:151], v[48:63]
	v_add_f32_e32 v2, v86, v2
	v_add_f32_e32 v2, v87, v2
	v_add_f32_e32 v2, v88, v2
	v_add_f32_e32 v2, v89, v2
	v_cvt_pk_bf16_f32 v158, v84, v85
	v_cvt_pk_bf16_f32 v159, v86, v87
	ds_read_b64_tr_b16 v[184:185], v0 offset:25600
	ds_read_b64_tr_b16 v[186:187], v0 offset:26112
	s_waitcnt lgkmcnt(11)
	v_mfma_f32_32x32x16_bf16 v[112:127], v[180:183], v[140:143], v[112:127]
	v_add_f32_e32 v2, v90, v2
	v_add_f32_e32 v2, v91, v2
	v_add_f32_e32 v2, v92, v2
	v_add_f32_e32 v2, v93, v2
	v_cvt_pk_bf16_f32 v152, v88, v89
	v_cvt_pk_bf16_f32 v153, v90, v91
	ds_read_b64_tr_b16 v[84:85], v0 offset:29696
	ds_read_b64_tr_b16 v[86:87], v0 offset:30208
	s_waitcnt lgkmcnt(12)
	v_mfma_f32_32x32x16_bf16 v[96:111], v[176:179], v[140:143], v[96:111]
	v_add_f32_e32 v2, v94, v2
	v_add_f32_e32 v2, v95, v2
	v_add_f32_e32 v2, v64, v2
	v_add_f32_e32 v2, v65, v2
	v_cvt_pk_bf16_f32 v154, v92, v93
	v_cvt_pk_bf16_f32 v155, v94, v95
	ds_read_b64_tr_b16 v[80:81], v0 offset:26624
	ds_read_b64_tr_b16 v[82:83], v0 offset:27136
	s_waitcnt lgkmcnt(13)
	v_mfma_f32_32x32x16_bf16 v[112:127], v[172:175], v[132:135], v[112:127]
	v_add_f32_e32 v2, v66, v2
	v_add_f32_e32 v2, v67, v2
	v_add_f32_e32 v2, v68, v2
	v_add_f32_e32 v2, v69, v2
	v_cvt_pk_bf16_f32 v144, v64, v65
	v_cvt_pk_bf16_f32 v145, v66, v67
	ds_read_b64_tr_b16 v[10:11], v0 offset:30720
	ds_read_b64_tr_b16 v[12:13], v0 offset:31232
	s_waitcnt lgkmcnt(14)
	v_mfma_f32_32x32x16_bf16 v[96:111], v[168:171], v[132:135], v[96:111]
	v_add_f32_e32 v2, v70, v2
	v_add_f32_e32 v2, v71, v2
	v_add_f32_e32 v2, v72, v2
	v_add_f32_e32 v2, v73, v2
	v_cvt_pk_bf16_f32 v146, v68, v69
	v_cvt_pk_bf16_f32 v147, v70, v71
	ds_read_b64_tr_b16 v[6:7], v0 offset:27648
	ds_read_b64_tr_b16 v[8:9], v0 offset:28160
	s_waitcnt lgkmcnt(14)
	v_mfma_f32_32x32x16_bf16 v[112:127], v[164:167], v[128:131], v[112:127]
	v_add_f32_e32 v2, v74, v2
	v_add_f32_e32 v2, v75, v2
	v_add_f32_e32 v2, v76, v2
	v_add_f32_e32 v14, v77, v2
	v_cvt_pk_bf16_f32 v136, v72, v73
	v_cvt_pk_bf16_f32 v137, v74, v75
	ds_read_b64_tr_b16 v[2:3], v0 offset:31744
	ds_read_b64_tr_b16 v[4:5], v0 offset:32256
	v_mfma_f32_32x32x16_bf16 v[96:111], v[160:163], v[128:131], v[96:111]
	v_add_f32_e32 v0, v78, v14
	v_add_f32_e32 v0, v79, v0
	v_cvt_pk_bf16_f32 v138, v76, v77
	v_cvt_pk_bf16_f32 v139, v78, v79
	v_lshl_add_u64 v[14:15], v[202:203], 0, s[26:27]
	s_add_i32 s8, s40, s46
	s_mov_b32 s9, m0
	s_mov_b32 m0, s8
	s_nop 0
	global_load_lds_dwordx4 v[14:15], off
	s_mov_b32 m0, s9
	v_lshl_add_u64 v[14:15], v[200:201], 0, s[26:27]
	s_add_i32 s8, s38, s47
	s_mov_b32 s9, m0
	s_mov_b32 m0, s8
	s_nop 0
	global_load_lds_dwordx4 v[14:15], off
	s_mov_b32 m0, s9
	v_max3_f32 v14, v112, v113, v114
	v_max3_f32 v15, v115, v116, v117
	v_max3_f32 v14, v14, v118, v119
	v_max3_f32 v15, v15, v120, v121
	v_max3_f32 v14, v14, v122, v123
	v_max3_f32 v15, v15, v124, v125
	v_max3_f32 v14, v14, v126, v127
	v_max3_f32 v15, v15, v96, v97
	v_max3_f32 v14, v14, v98, v99
	v_max3_f32 v15, v15, v100, v101
	v_max3_f32 v14, v14, v102, v103
	v_max3_f32 v15, v15, v104, v105
	v_max3_f32 v14, v14, v106, v107
	v_max3_f32 v15, v15, v108, v109
	v_max3_f32 v64, v14, v110, v111
	v_add_f32_e32 v14, v223, v0
	v_max_f32_e32 v0, v64, v15
	v_mov_b32_e32 v15, v0
	s_nop 1
	v_permlane32_swap_b32_e32 v0, v15
	v_max_f32_e32 v0, v0, v15
	v_cmp_lt_f32_e32 vcc, s53, v0
	s_cmp_lg_u64 vcc, 0
	s_cselect_b64 s[8:9], -1, 0
	s_cbranch_vccnz .LBB0_1555
.LBB0_1548:
	s_waitcnt lgkmcnt(14)
	v_mfma_f32_32x32x16_bf16 v[32:47], v[156:159], v[192:195], v[32:47]
	v_exp_f32_e32 v112, v112
	v_exp_f32_e32 v113, v113
	v_exp_f32_e32 v114, v114
	v_exp_f32_e32 v115, v115
	s_waitcnt lgkmcnt(12)
	v_mfma_f32_32x32x16_bf16 v[16:31], v[156:159], v[188:191], v[16:31]
	v_exp_f32_e32 v116, v116
	v_exp_f32_e32 v117, v117
	v_exp_f32_e32 v118, v118
	v_exp_f32_e32 v119, v119
	v_add_u32_e32 v0, s38, v220
	ds_read_b128 v[64:67], v0
	ds_read_b128 v[160:163], v0 offset:512
	s_waitcnt lgkmcnt(12)
	v_mfma_f32_32x32x16_bf16 v[32:47], v[152:155], v[184:187], v[32:47]
	v_exp_f32_e32 v120, v120
	v_exp_f32_e32 v121, v121
	v_exp_f32_e32 v122, v122
	v_exp_f32_e32 v123, v123
	ds_read_b128 v[192:195], v0 offset:2048
	ds_read_b128 v[184:187], v0 offset:2560
	s_waitcnt lgkmcnt(12)
	v_mfma_f32_32x32x16_bf16 v[16:31], v[152:155], v[84:87], v[16:31]
	v_exp_f32_e32 v124, v124
	v_exp_f32_e32 v125, v125
	v_exp_f32_e32 v126, v126
	v_exp_f32_e32 v127, v127
	ds_read_b128 v[188:191], v0 offset:4096
	ds_read_b128 v[176:179], v0 offset:4608
	s_waitcnt lgkmcnt(12)
	v_mfma_f32_32x32x16_bf16 v[32:47], v[144:147], v[80:83], v[32:47]
	v_exp_f32_e32 v96, v96
	v_exp_f32_e32 v97, v97
	v_exp_f32_e32 v98, v98
	v_exp_f32_e32 v99, v99
	ds_read_b128 v[180:183], v0 offset:6144
	ds_read_b128 v[172:175], v0 offset:6656
	s_waitcnt lgkmcnt(12)
	v_mfma_f32_32x32x16_bf16 v[16:31], v[144:147], v[10:13], v[16:31]
	v_exp_f32_e32 v100, v100
	v_exp_f32_e32 v101, v101
	v_exp_f32_e32 v102, v102
	v_exp_f32_e32 v103, v103
	s_waitcnt lgkmcnt(10)
	v_mfma_f32_32x32x16_bf16 v[32:47], v[136:139], v[6:9], v[32:47]
	v_exp_f32_e32 v104, v104
	v_exp_f32_e32 v105, v105
	v_exp_f32_e32 v106, v106
	v_exp_f32_e32 v107, v107
	s_waitcnt lgkmcnt(8)
	v_mfma_f32_32x32x16_bf16 v[16:31], v[136:139], v[2:5], v[16:31]
	v_exp_f32_e32 v108, v108
	v_exp_f32_e32 v109, v109
	v_exp_f32_e32 v110, v110
	v_exp_f32_e32 v111, v111
	s_waitcnt vmcnt(2) lgkmcnt(0)
	s_barrier
	v_mfma_f32_32x32x16_bf16 v[80:95], v[64:67], v[148:151], v[48:63]
	s_andn2_b64 vcc, exec, s[8:9]
	v_add_u32_e32 v0, s48, v222
	s_cbranch_vccnz .LBB0_1550
	s_waitcnt lgkmcnt(0)
	ds_read_b128 v[2:5], v0 offset:49248
	ds_read_b128 v[6:9], v0 offset:49216
	ds_read_b128 v[10:13], v0 offset:49184
	ds_read_b128 v[68:71], v0 offset:49152
	s_waitcnt lgkmcnt(3)
	v_pk_mul_f32 v[44:45], v[44:45], v[2:3]
	s_waitcnt lgkmcnt(2)
	v_pk_mul_f32 v[40:41], v[40:41], v[6:7]
	s_waitcnt lgkmcnt(1)
	v_pk_mul_f32 v[36:37], v[36:37], v[10:11]
	v_pk_mul_f32 v[46:47], v[46:47], v[4:5]
	v_pk_mul_f32 v[42:43], v[42:43], v[8:9]
	v_pk_mul_f32 v[38:39], v[38:39], v[12:13]
	s_waitcnt lgkmcnt(0)
	v_pk_mul_f32 v[34:35], v[34:35], v[70:71]
	v_pk_mul_f32 v[32:33], v[32:33], v[68:69]
	v_pk_mul_f32 v[28:29], v[28:29], v[2:3]
	v_pk_mul_f32 v[24:25], v[24:25], v[6:7]
	v_pk_mul_f32 v[20:21], v[20:21], v[10:11]
	v_pk_mul_f32 v[30:31], v[30:31], v[4:5]
	v_pk_mul_f32 v[26:27], v[26:27], v[8:9]
	v_pk_mul_f32 v[22:23], v[22:23], v[12:13]
	v_pk_mul_f32 v[18:19], v[18:19], v[70:71]
	v_pk_mul_f32 v[16:17], v[16:17], v[68:69]
.LBB0_1550:
	s_add_i32 s8, s38, 0x2000
	s_cmpk_lg_i32 s38, 0x4000
	s_cselect_b32 s13, s8, 0
	v_add_u32_e32 v4, s40, v221
	ds_read_b64_tr_b16 v[168:169], v4 offset:24576
	ds_read_b64_tr_b16 v[170:171], v4 offset:25088
	s_waitcnt lgkmcnt(9)
	v_add_f32_e32 v2, v112, v113
	v_add_f32_e32 v2, v114, v2
	v_add_f32_e32 v2, v115, v2
	v_add_f32_e32 v2, v116, v2
	v_add_f32_e32 v2, v117, v2
	v_cvt_pk_bf16_f32 v156, v112, v113
	v_cvt_pk_bf16_f32 v157, v114, v115
	ds_read_b64_tr_b16 v[164:165], v4 offset:28672
	ds_read_b64_tr_b16 v[166:167], v4 offset:29184
	s_waitcnt lgkmcnt(10)
	v_mfma_f32_32x32x16_bf16 v[64:79], v[160:163], v[148:151], v[48:63]
	v_add_f32_e32 v2, v118, v2
	v_add_f32_e32 v2, v119, v2
	v_add_f32_e32 v2, v120, v2
	v_add_f32_e32 v2, v121, v2
	v_cvt_pk_bf16_f32 v158, v116, v117
	v_cvt_pk_bf16_f32 v159, v118, v119
	ds_read_b64_tr_b16 v[160:161], v4 offset:25600
	ds_read_b64_tr_b16 v[162:163], v4 offset:26112
	s_waitcnt lgkmcnt(11)
	v_mfma_f32_32x32x16_bf16 v[80:95], v[192:195], v[140:143], v[80:95]
	v_add_f32_e32 v2, v122, v2
	v_add_f32_e32 v2, v123, v2
	v_add_f32_e32 v2, v124, v2
	v_add_f32_e32 v2, v125, v2
	v_cvt_pk_bf16_f32 v152, v120, v121
	v_cvt_pk_bf16_f32 v153, v122, v123
	ds_read_b64_tr_b16 v[116:117], v4 offset:29696
	ds_read_b64_tr_b16 v[118:119], v4 offset:30208
	s_waitcnt lgkmcnt(12)
	v_mfma_f32_32x32x16_bf16 v[64:79], v[184:187], v[140:143], v[64:79]
	v_add_f32_e32 v2, v126, v2
	v_add_f32_e32 v2, v127, v2
	v_add_f32_e32 v2, v96, v2
	v_add_f32_e32 v2, v97, v2
	v_cvt_pk_bf16_f32 v154, v124, v125
	v_cvt_pk_bf16_f32 v155, v126, v127
	ds_read_b64_tr_b16 v[112:113], v4 offset:26624
	ds_read_b64_tr_b16 v[114:115], v4 offset:27136
	s_waitcnt lgkmcnt(13)
	v_mfma_f32_32x32x16_bf16 v[80:95], v[188:191], v[132:135], v[80:95]
	v_add_f32_e32 v2, v98, v2
	v_add_f32_e32 v2, v99, v2
	v_add_f32_e32 v2, v100, v2
	v_add_f32_e32 v2, v101, v2
	v_cvt_pk_bf16_f32 v144, v96, v97
	v_cvt_pk_bf16_f32 v145, v98, v99
	ds_read_b64_tr_b16 v[10:11], v4 offset:30720
	ds_read_b64_tr_b16 v[12:13], v4 offset:31232
	s_waitcnt lgkmcnt(14)
	v_mfma_f32_32x32x16_bf16 v[64:79], v[176:179], v[132:135], v[64:79]
	v_add_f32_e32 v2, v102, v2
	v_add_f32_e32 v2, v103, v2
	v_add_f32_e32 v2, v104, v2
	v_add_f32_e32 v2, v105, v2
	v_cvt_pk_bf16_f32 v146, v100, v101
	v_cvt_pk_bf16_f32 v147, v102, v103
	ds_read_b64_tr_b16 v[6:7], v4 offset:27648
	ds_read_b64_tr_b16 v[8:9], v4 offset:28160
	s_waitcnt lgkmcnt(14)
	v_mfma_f32_32x32x16_bf16 v[80:95], v[180:183], v[128:131], v[80:95]
	v_add_f32_e32 v2, v106, v2
	v_add_f32_e32 v2, v107, v2
	v_add_f32_e32 v2, v108, v2
	v_add_f32_e32 v15, v109, v2
	v_cvt_pk_bf16_f32 v136, v104, v105
	v_cvt_pk_bf16_f32 v137, v106, v107
	ds_read_b64_tr_b16 v[2:3], v4 offset:31744
	ds_read_b64_tr_b16 v[4:5], v4 offset:32256
	v_mfma_f32_32x32x16_bf16 v[64:79], v[172:175], v[128:131], v[64:79]
	v_add_f32_e32 v15, v110, v15
	v_add_f32_e32 v15, v111, v15
	v_cvt_pk_bf16_f32 v138, v108, v109
	v_cvt_pk_bf16_f32 v139, v110, v111
	v_max3_f32 v96, v80, v81, v82
	v_max3_f32 v97, v83, v84, v85
	v_max3_f32 v96, v96, v86, v87
	v_max3_f32 v97, v97, v88, v89
	v_max3_f32 v96, v96, v90, v91
	v_max3_f32 v97, v97, v92, v93
	v_max3_f32 v96, v96, v94, v95
	v_add_f32_e32 v223, v14, v15
	s_nop 0
	v_max3_f32 v97, v97, v64, v65
	v_max3_f32 v96, v96, v66, v67
	v_max3_f32 v97, v97, v68, v69
	v_max3_f32 v96, v96, v70, v71
	v_max3_f32 v97, v97, v72, v73
	v_max3_f32 v96, v96, v74, v75
	v_max3_f32 v97, v97, v76, v77
	v_max3_f32 v96, v96, v78, v79
	v_max_f32_e32 v14, v96, v97
	v_mov_b32_e32 v15, v14
	s_nop 1
	v_permlane32_swap_b32_e32 v14, v15
	s_add_i32 s8, s38, s46
	s_mov_b32 s9, m0
	s_mov_b32 m0, s8
	s_nop 0
	global_load_lds_dwordx4 v[202:203], off
	s_mov_b32 m0, s9
	v_max_f32_e32 v14, v14, v15
	s_add_i32 s8, s13, s47
	s_mov_b32 s9, m0
	s_mov_b32 m0, s8
	s_nop 0
	global_load_lds_dwordx4 v[200:201], off
	s_mov_b32 m0, s9
	v_cmp_lt_f32_e32 vcc, s53, v14
	s_cmp_lg_u64 vcc, 0
	s_cselect_b64 s[8:9], -1, 0
	s_cbranch_vccnz .LBB0_1558
.LBB0_1551:
	s_waitcnt lgkmcnt(14)
	v_mfma_f32_32x32x16_bf16 v[32:47], v[156:159], v[168:171], v[32:47]
	v_exp_f32_e32 v80, v80
	v_exp_f32_e32 v81, v81
	v_exp_f32_e32 v82, v82
	v_exp_f32_e32 v83, v83
	s_waitcnt lgkmcnt(12)
	v_mfma_f32_32x32x16_bf16 v[16:31], v[156:159], v[164:167], v[16:31]
	v_exp_f32_e32 v84, v84
	v_exp_f32_e32 v85, v85
	v_exp_f32_e32 v86, v86
	v_exp_f32_e32 v87, v87
	v_add_u32_e32 v14, s13, v220
	ds_read_b128 v[188:191], v14
	ds_read_b128 v[184:187], v14 offset:512
	s_waitcnt lgkmcnt(12)
	v_mfma_f32_32x32x16_bf16 v[32:47], v[152:155], v[160:163], v[32:47]
	v_exp_f32_e32 v88, v88
	v_exp_f32_e32 v89, v89
	v_exp_f32_e32 v90, v90
	v_exp_f32_e32 v91, v91
	ds_read_b128 v[180:183], v14 offset:2048
	ds_read_b128 v[176:179], v14 offset:2560
	s_waitcnt lgkmcnt(12)
	v_mfma_f32_32x32x16_bf16 v[16:31], v[152:155], v[116:119], v[16:31]
	v_exp_f32_e32 v92, v92
	v_exp_f32_e32 v93, v93
	v_exp_f32_e32 v94, v94
	v_exp_f32_e32 v95, v95
	ds_read_b128 v[172:175], v14 offset:4096
	ds_read_b128 v[168:171], v14 offset:4608
	s_waitcnt lgkmcnt(12)
	v_mfma_f32_32x32x16_bf16 v[32:47], v[144:147], v[112:115], v[32:47]
	v_exp_f32_e32 v64, v64
	v_exp_f32_e32 v65, v65
	v_exp_f32_e32 v66, v66
	v_exp_f32_e32 v67, v67
	ds_read_b128 v[164:167], v14 offset:6144
	ds_read_b128 v[160:163], v14 offset:6656
	s_waitcnt lgkmcnt(12)
	v_mfma_f32_32x32x16_bf16 v[16:31], v[144:147], v[10:13], v[16:31]
	v_exp_f32_e32 v68, v68
	v_exp_f32_e32 v69, v69
	v_exp_f32_e32 v70, v70
	v_exp_f32_e32 v71, v71
	s_waitcnt lgkmcnt(10)
	v_mfma_f32_32x32x16_bf16 v[32:47], v[136:139], v[6:9], v[32:47]
	v_exp_f32_e32 v72, v72
	v_exp_f32_e32 v73, v73
	v_exp_f32_e32 v74, v74
	v_exp_f32_e32 v75, v75
	s_waitcnt lgkmcnt(8)
	v_mfma_f32_32x32x16_bf16 v[16:31], v[136:139], v[2:5], v[16:31]
	v_exp_f32_e32 v76, v76
	v_exp_f32_e32 v77, v77
	v_exp_f32_e32 v78, v78
	v_exp_f32_e32 v79, v79
	s_waitcnt vmcnt(2) lgkmcnt(0)
	s_barrier
	v_mfma_f32_32x32x16_bf16 v[112:127], v[188:191], v[148:151], v[48:63]
	s_andn2_b64 vcc, exec, s[8:9]
	s_cbranch_vccnz .LBB0_1553
	s_waitcnt lgkmcnt(0)
	ds_read_b128 v[2:5], v0 offset:49248
	ds_read_b128 v[6:9], v0 offset:49216
	ds_read_b128 v[10:13], v0 offset:49184
	ds_read_b128 v[96:99], v0 offset:49152
	s_waitcnt lgkmcnt(3)
	v_pk_mul_f32 v[44:45], v[44:45], v[2:3]
	s_waitcnt lgkmcnt(2)
	v_pk_mul_f32 v[40:41], v[40:41], v[6:7]
	s_waitcnt lgkmcnt(1)
	v_pk_mul_f32 v[36:37], v[36:37], v[10:11]
	v_pk_mul_f32 v[46:47], v[46:47], v[4:5]
	v_pk_mul_f32 v[42:43], v[42:43], v[8:9]
	v_pk_mul_f32 v[38:39], v[38:39], v[12:13]
	s_waitcnt lgkmcnt(0)
	v_pk_mul_f32 v[34:35], v[34:35], v[98:99]
	v_pk_mul_f32 v[32:33], v[32:33], v[96:97]
	v_pk_mul_f32 v[28:29], v[28:29], v[2:3]
	v_pk_mul_f32 v[24:25], v[24:25], v[6:7]
	v_pk_mul_f32 v[20:21], v[20:21], v[10:11]
	v_pk_mul_f32 v[30:31], v[30:31], v[4:5]
	v_pk_mul_f32 v[26:27], v[26:27], v[8:9]
	v_pk_mul_f32 v[22:23], v[22:23], v[12:13]
	v_pk_mul_f32 v[18:19], v[18:19], v[98:99]
	v_pk_mul_f32 v[16:17], v[16:17], v[96:97]
